# also de-serialized retention staging loads (retS: 4 K + 6 V loads in flight; retO: state chunk pairs), ctab kn_b max via 16 wide loads
# speedup vs baseline: 1.0341x; 1.0008x over previous
.LBB0_64:
	s_mov_b64 s[0:1], s[12:13]
	s_mov_b64 s[0:1], s[14:15]
	s_mov_b64 s[0:1], s[16:17]
	s_mov_b64 s[0:1], s[18:19]
	s_mov_b64 s[0:1], s[20:21]
	s_mov_b64 s[0:1], s[22:23]
	s_mov_b64 s[0:1], s[24:25]
	s_mov_b64 s[0:1], s[26:27]
	v_readlane_b32 s36, v243, 22
	v_readlane_b32 s37, v243, 23
	s_mov_b64 s[0:1], s[36:37]
	v_readlane_b32 s38, v243, 24
	v_readlane_b32 s39, v243, 25
	s_mov_b64 s[0:1], s[38:39]
	v_readlane_b32 s40, v243, 26
	v_readlane_b32 s41, v243, 27
	s_mov_b64 s[0:1], s[40:41]
	v_readlane_b32 s42, v243, 28
	v_readlane_b32 s43, v243, 29
	s_mov_b64 s[0:1], s[42:43]
	v_readlane_b32 s44, v243, 30
	v_readlane_b32 s45, v243, 31
	s_mov_b64 s[0:1], s[44:45]
	v_readlane_b32 s46, v243, 32
	v_readlane_b32 s47, v243, 33
	s_mov_b64 s[0:1], s[46:47]
	v_readlane_b32 s48, v243, 34
	v_readlane_b32 s49, v243, 35
	s_mov_b64 s[0:1], s[48:49]
	v_readlane_b32 s50, v243, 36
	v_readlane_b32 s51, v243, 37
	s_mov_b64 s[0:1], s[50:51]
	s_mov_b64 s[0:1], s[52:53]
	s_mov_b64 s[0:1], s[54:55]
	s_mov_b64 s[0:1], s[56:57]
	s_mov_b64 s[0:1], s[58:59]
	s_mov_b64 s[0:1], s[60:61]
	s_mov_b64 s[0:1], s[62:63]
	s_mov_b64 s[8:9], s[64:65]
	s_mov_b64 s[0:1], s[66:67]
	v_readlane_b32 s36, v243, 5
	v_readlane_b32 s37, v243, 6
	s_mov_b64 s[0:1], s[36:37]
	v_readlane_b32 s38, v243, 7
	v_readlane_b32 s39, v243, 8
	s_mov_b64 s[0:1], s[38:39]
	v_readlane_b32 s40, v243, 9
	v_readlane_b32 s41, v243, 10
	s_mov_b64 s[0:1], s[40:41]
	v_readlane_b32 s68, v243, 1
	v_readlane_b32 s42, v243, 11
	v_readlane_b32 s43, v243, 12
	v_readlane_b32 s69, v243, 2
	v_readlane_b32 s70, v243, 3
	v_readlane_b32 s71, v243, 4
	s_mov_b64 s[0:1], s[42:43]
	s_mov_b64 s[30:31], s[68:69]
	s_mov_b64 s[4:5], s[70:71]
	s_add_i32 s10, s2, s3
	s_ashr_i32 s4, s10, 7
	s_and_b32 s28, s10, 31
	s_ashr_i32 s5, s4, 31
	s_lshl_b64 s[68:69], s[4:5], 12
	s_lshl_b32 s5, s28, 7
	s_or_b32 s5, s68, s5
	s_bfe_u32 s29, s10, 0x20005
	s_mul_i32 s10, s69, 0x1e00
	s_mul_hi_u32 s68, s5, 0x1e00
	s_add_i32 s68, s68, s10
	s_mulk_i32 s5, 0x1e00
	s_add_u32 s8, s8, s5
	s_addc_u32 s9, s9, s68
	s_add_u32 s68, s98, s29
	s_addc_u32 s69, s99, 0
	v_mov_b32_e32 v51, v200
	s_lshl_b64 s[68:69], s[68:69], 2
	s_movk_i32 s38, 0x1e00
	s_add_u32 s30, s30, s68
	v_ashrrev_i32_e32 v5, 3, v51
	v_mov_b64_e32 v[2:3], s[8:9]
	s_addc_u32 s31, s31, s69
	v_lshlrev_b32_e32 v0, 4, v51
	v_mad_i64_i32 v[8:9], s[8:9], v5, s38, v[2:3]
	s_lshl_b32 s10, s29, 7
	v_and_b32_e32 v0, 0x70, v0
	v_lshl_add_u64 v[8:9], v[8:9], 0, s[10:11]
	global_load_dword v7, v1, s[30:31] offset:8
	global_load_dword v6, v1, s[30:31] offset:24
	v_lshl_add_u64 v[8:9], v[8:9], 0, v[0:1]
	s_movk_i32 s5, 0x1000
	v_add_co_u32_e32 v8, vcc, s5, v8
	v_sub_u32_e32 v12, 0x7f, v5
	s_nop 0
	v_addc_co_u32_e32 v9, vcc, 0, v9, vcc
	v_add_co_u32_e32 v130, vcc, 0x3c000, v8
	s_nop 1
	v_addc_co_u32_e32 v131, vcc, 0, v9, vcc
	v_add_co_u32_e32 v132, vcc, 0x78000, v8
	s_nop 1
	v_addc_co_u32_e32 v133, vcc, 0, v9, vcc
	v_add_co_u32_e32 v134, vcc, 0xb4000, v8
	s_nop 1
	v_addc_co_u32_e32 v135, vcc, 0, v9, vcc
	global_load_dwordx4 v[8:11], v[8:9], off offset:1536
	global_load_dwordx4 v[136:139], v[130:131], off offset:1536
	global_load_dwordx4 v[140:143], v[132:133], off offset:1536
	global_load_dwordx4 v[144:147], v[134:135], off offset:1536
	v_cvt_f32_i32_e32 v12, v12
	v_cvt_f32_i32_e32 v13, v5
	s_movk_i32 s30, 0x90
	s_mov_b32 s31, 0x2aaaaaab
	s_movk_i32 s36, 0xd0
	v_lshlrev_b32_e32 v4, 3, v51
	v_and_b32_e32 v4, 24, v4
	s_waitcnt vmcnt(5)
	v_mul_f32_e32 v12, v7, v12
	v_exp_f32_e32 v12, v12
	s_waitcnt vmcnt(4)
	v_mul_f32_e32 v13, v6, v13
	v_exp_f32_e32 v14, v13
	s_waitcnt vmcnt(3)
	v_lshlrev_b32_e32 v16, 16, v8
	v_and_b32_e32 v17, 0xffff0000, v8
	v_pk_mul_f32 v[18:19], v[12:13], v[16:17] op_sel_hi:[0,1]
	v_cvt_pk_bf16_f32 v8, v18, v19
	v_lshlrev_b32_e32 v18, 16, v9
	v_and_b32_e32 v19, 0xffff0000, v9
	v_pk_mul_f32 v[20:21], v[12:13], v[18:19] op_sel_hi:[0,1]
	v_cvt_pk_bf16_f32 v9, v20, v21
	v_lshlrev_b32_e32 v20, 16, v10
	v_and_b32_e32 v21, 0xffff0000, v10
	v_pk_mul_f32 v[22:23], v[12:13], v[20:21] op_sel_hi:[0,1]
	v_cvt_pk_bf16_f32 v10, v22, v23
	v_lshlrev_b32_e32 v22, 16, v11
	v_and_b32_e32 v23, 0xffff0000, v11
	v_pk_mul_f32 v[12:13], v[12:13], v[22:23] op_sel_hi:[0,1]
	v_cvt_pk_bf16_f32 v11, v12, v13
	v_mad_u64_u32 v[12:13], s[8:9], v5, s30, v[0:1]
	ds_write_b128 v12, v[8:11]
	v_pk_mul_f32 v[8:9], v[14:15], v[16:17] op_sel_hi:[0,1]
	v_pk_mul_f32 v[10:11], v[14:15], v[18:19] op_sel_hi:[0,1]
	v_cvt_pk_bf16_f32 v8, v8, v9
	v_cvt_pk_bf16_f32 v9, v10, v11
	v_pk_mul_f32 v[10:11], v[14:15], v[20:21] op_sel_hi:[0,1]
	v_pk_mul_f32 v[14:15], v[14:15], v[22:23] op_sel_hi:[0,1]
	v_add_u32_e32 v5, 0x100, v51
	v_cvt_pk_bf16_f32 v10, v10, v11
	v_cvt_pk_bf16_f32 v11, v14, v15
	v_ashrrev_i32_e32 v15, 3, v5
	ds_write_b128 v12, v[8:11] offset:18432
	v_mad_i64_i32 v[8:9], s[8:9], v15, s38, v[2:3]
	v_lshl_add_u64 v[8:9], v[8:9], 0, s[10:11]
	v_lshl_add_u64 v[8:9], v[8:9], 0, v[0:1]
	v_add_co_u32_e32 v8, vcc, s5, v8
	v_sub_u32_e32 v12, 0x7f, v15
	s_nop 0
	v_addc_co_u32_e32 v9, vcc, 0, v9, vcc
	v_cvt_f32_i32_e32 v12, v12
	v_cvt_f32_i32_e32 v13, v15
	v_mul_f32_e32 v12, v7, v12
	v_exp_f32_e32 v12, v12
	v_mul_f32_e32 v13, v6, v13
	v_exp_f32_e32 v14, v13
	s_waitcnt vmcnt(2)
	v_lshlrev_b32_e32 v16, 16, v136
	v_and_b32_e32 v17, 0xffff0000, v136
	v_pk_mul_f32 v[18:19], v[12:13], v[16:17] op_sel_hi:[0,1]
	v_cvt_pk_bf16_f32 v8, v18, v19
	v_lshlrev_b32_e32 v18, 16, v137
	v_and_b32_e32 v19, 0xffff0000, v137
	v_pk_mul_f32 v[20:21], v[12:13], v[18:19] op_sel_hi:[0,1]
	v_cvt_pk_bf16_f32 v9, v20, v21
	v_lshlrev_b32_e32 v20, 16, v138
	v_and_b32_e32 v21, 0xffff0000, v138
	v_pk_mul_f32 v[22:23], v[12:13], v[20:21] op_sel_hi:[0,1]
	v_cvt_pk_bf16_f32 v10, v22, v23
	v_lshlrev_b32_e32 v22, 16, v139
	v_and_b32_e32 v23, 0xffff0000, v139
	v_pk_mul_f32 v[12:13], v[12:13], v[22:23] op_sel_hi:[0,1]
	v_cvt_pk_bf16_f32 v11, v12, v13
	v_mad_u64_u32 v[12:13], s[8:9], v15, s30, v[0:1]
	ds_write_b128 v12, v[8:11]
	v_pk_mul_f32 v[8:9], v[14:15], v[16:17] op_sel_hi:[0,1]
	v_pk_mul_f32 v[10:11], v[14:15], v[18:19] op_sel_hi:[0,1]
	v_cvt_pk_bf16_f32 v8, v8, v9
	v_cvt_pk_bf16_f32 v9, v10, v11
	v_pk_mul_f32 v[10:11], v[14:15], v[20:21] op_sel_hi:[0,1]
	v_pk_mul_f32 v[14:15], v[14:15], v[22:23] op_sel_hi:[0,1]
	v_cvt_pk_bf16_f32 v10, v10, v11
	v_cvt_pk_bf16_f32 v11, v14, v15
	ds_write_b128 v12, v[8:11] offset:18432
	v_add_u32_e32 v8, 0x200, v51
	v_ashrrev_i32_e32 v9, 3, v8
	v_mad_i64_i32 v[10:11], s[8:9], v9, s38, v[2:3]
	v_lshl_add_u64 v[10:11], v[10:11], 0, s[10:11]
	v_lshl_add_u64 v[10:11], v[10:11], 0, v[0:1]
	v_add_co_u32_e32 v10, vcc, s5, v10
	v_sub_u32_e32 v14, 0x7f, v9
	s_nop 0
	v_addc_co_u32_e32 v11, vcc, 0, v11, vcc
	v_cvt_f32_i32_e32 v14, v14
	v_cvt_f32_i32_e32 v15, v9
	v_mul_f32_e32 v14, v7, v14
	v_exp_f32_e32 v14, v14
	v_mul_f32_e32 v15, v6, v15
	v_exp_f32_e32 v16, v15
	s_waitcnt vmcnt(1)
	v_lshlrev_b32_e32 v18, 16, v140
	v_and_b32_e32 v19, 0xffff0000, v140
	v_pk_mul_f32 v[20:21], v[14:15], v[18:19] op_sel_hi:[0,1]
	v_cvt_pk_bf16_f32 v10, v20, v21
	v_lshlrev_b32_e32 v20, 16, v141
	v_and_b32_e32 v21, 0xffff0000, v141
	v_pk_mul_f32 v[22:23], v[14:15], v[20:21] op_sel_hi:[0,1]
	v_cvt_pk_bf16_f32 v11, v22, v23
	v_lshlrev_b32_e32 v22, 16, v142
	v_and_b32_e32 v23, 0xffff0000, v142
	v_pk_mul_f32 v[24:25], v[14:15], v[22:23] op_sel_hi:[0,1]
	v_cvt_pk_bf16_f32 v12, v24, v25
	v_lshlrev_b32_e32 v24, 16, v143
	v_and_b32_e32 v25, 0xffff0000, v143
	v_pk_mul_f32 v[14:15], v[14:15], v[24:25] op_sel_hi:[0,1]
	v_cvt_pk_bf16_f32 v13, v14, v15
	v_mad_u64_u32 v[14:15], s[8:9], v9, s30, v[0:1]
	ds_write_b128 v14, v[10:13]
	v_pk_mul_f32 v[10:11], v[16:17], v[18:19] op_sel_hi:[0,1]
	v_pk_mul_f32 v[12:13], v[16:17], v[20:21] op_sel_hi:[0,1]
	v_cvt_pk_bf16_f32 v10, v10, v11
	v_cvt_pk_bf16_f32 v11, v12, v13
	v_pk_mul_f32 v[12:13], v[16:17], v[22:23] op_sel_hi:[0,1]
	v_pk_mul_f32 v[16:17], v[16:17], v[24:25] op_sel_hi:[0,1]
	v_add_u32_e32 v24, 0x300, v51
	v_cvt_pk_bf16_f32 v12, v12, v13
	v_cvt_pk_bf16_f32 v13, v16, v17
	v_ashrrev_i32_e32 v9, 3, v24
	ds_write_b128 v14, v[10:13] offset:18432
	v_mad_i64_i32 v[10:11], s[8:9], v9, s38, v[2:3]
	v_lshl_add_u64 v[10:11], v[10:11], 0, s[10:11]
	v_lshl_add_u64 v[10:11], v[10:11], 0, v[0:1]
	v_add_co_u32_e32 v10, vcc, s5, v10
	v_sub_u32_e32 v14, 0x7f, v9
	s_nop 0
	v_addc_co_u32_e32 v11, vcc, 0, v11, vcc
	v_cvt_f32_i32_e32 v14, v14
	s_mul_i32 s10, s29, 0xc0
	v_mul_f32_e32 v7, v7, v14
	v_exp_f32_e32 v14, v7
	v_cvt_f32_i32_e32 v7, v9
	v_mul_f32_e32 v6, v6, v7
	v_exp_f32_e32 v6, v6
	s_waitcnt vmcnt(0)
	v_lshlrev_b32_e32 v16, 16, v144
	v_and_b32_e32 v17, 0xffff0000, v144
	v_pk_mul_f32 v[18:19], v[14:15], v[16:17] op_sel_hi:[0,1]
	v_cvt_pk_bf16_f32 v10, v18, v19
	v_lshlrev_b32_e32 v18, 16, v145
	v_and_b32_e32 v19, 0xffff0000, v145
	v_pk_mul_f32 v[20:21], v[14:15], v[18:19] op_sel_hi:[0,1]
	v_cvt_pk_bf16_f32 v11, v20, v21
	v_lshlrev_b32_e32 v20, 16, v146
	v_and_b32_e32 v21, 0xffff0000, v146
	v_pk_mul_f32 v[22:23], v[14:15], v[20:21] op_sel_hi:[0,1]
	v_cvt_pk_bf16_f32 v12, v22, v23
	v_lshlrev_b32_e32 v22, 16, v147
	v_and_b32_e32 v23, 0xffff0000, v147
	v_pk_mul_f32 v[14:15], v[14:15], v[22:23] op_sel_hi:[0,1]
	v_cvt_pk_bf16_f32 v13, v14, v15
	v_mad_u64_u32 v[14:15], s[8:9], v9, s30, v[0:1]
	ds_write_b128 v14, v[10:13]
	v_pk_mul_f32 v[10:11], v[6:7], v[16:17] op_sel_hi:[0,1]
	v_pk_mul_f32 v[12:13], v[6:7], v[18:19] op_sel_hi:[0,1]
	v_cvt_pk_bf16_f32 v10, v10, v11
	v_cvt_pk_bf16_f32 v11, v12, v13
	v_pk_mul_f32 v[12:13], v[6:7], v[20:21] op_sel_hi:[0,1]
	v_pk_mul_f32 v[6:7], v[6:7], v[22:23] op_sel_hi:[0,1]
	v_mul_hi_i32 v0, v51, s31
	v_cvt_pk_bf16_f32 v12, v12, v13
	v_cvt_pk_bf16_f32 v13, v6, v7
	v_lshrrev_b32_e32 v6, 31, v0
	v_ashrrev_i32_e32 v0, 1, v0
	v_add_u32_e32 v0, v0, v6
	v_mul_lo_u32 v6, v0, 12
	v_sub_u32_e32 v9, v51, v6
	ds_write_b128 v14, v[10:13] offset:18432
	v_mad_i64_i32 v[6:7], s[8:9], v0, s38, v[2:3]
	v_lshlrev_b32_e32 v10, 3, v9
	v_lshl_add_u64 v[6:7], v[6:7], 0, s[10:11]
	v_ashrrev_i32_e32 v11, 31, v10
	v_lshl_add_u64 v[6:7], v[10:11], 1, v[6:7]
	v_add_co_u32_e32 v6, vcc, s5, v6
	v_mul_lo_u32 v0, v0, s36
	s_nop 0
	v_addc_co_u32_e32 v7, vcc, 0, v7, vcc
	global_load_dwordx4 v[148:151], v[6:7], off offset:2048
	v_lshl_add_u32 v172, v9, 4, v0
	v_mul_hi_i32 v0, v5, s31
	v_lshrrev_b32_e32 v6, 31, v0
	v_ashrrev_i32_e32 v0, 1, v0
	v_add_u32_e32 v0, v0, v6
	v_mul_lo_u32 v6, v0, 12
	v_sub_u32_e32 v5, v5, v6
	v_mad_i64_i32 v[6:7], s[8:9], v0, s38, v[2:3]
	v_lshlrev_b32_e32 v10, 3, v5
	v_lshl_add_u64 v[6:7], v[6:7], 0, s[10:11]
	v_ashrrev_i32_e32 v11, 31, v10
	v_lshl_add_u64 v[6:7], v[10:11], 1, v[6:7]
	v_add_co_u32_e32 v6, vcc, s5, v6
	v_mul_lo_u32 v0, v0, s36
	s_nop 0
	v_addc_co_u32_e32 v7, vcc, 0, v7, vcc
	global_load_dwordx4 v[152:155], v[6:7], off offset:2048
	v_lshl_add_u32 v173, v5, 4, v0
	v_mul_hi_i32 v0, v8, s31
	v_lshrrev_b32_e32 v5, 31, v0
	v_ashrrev_i32_e32 v0, 1, v0
	v_add_u32_e32 v0, v0, v5
	v_mul_lo_u32 v5, v0, 12
	v_sub_u32_e32 v5, v8, v5
	v_mad_i64_i32 v[6:7], s[8:9], v0, s38, v[2:3]
	v_lshlrev_b32_e32 v8, 3, v5
	v_lshl_add_u64 v[6:7], v[6:7], 0, s[10:11]
	v_ashrrev_i32_e32 v9, 31, v8
	v_lshl_add_u64 v[6:7], v[8:9], 1, v[6:7]
	v_add_co_u32_e32 v6, vcc, s5, v6
	v_mul_lo_u32 v0, v0, s36
	s_nop 0
	v_addc_co_u32_e32 v7, vcc, 0, v7, vcc
	global_load_dwordx4 v[156:159], v[6:7], off offset:2048
	v_lshl_add_u32 v174, v5, 4, v0
	v_mul_hi_i32 v0, v24, s31
	v_lshrrev_b32_e32 v5, 31, v0
	v_ashrrev_i32_e32 v0, 1, v0
	v_add_u32_e32 v0, v0, v5
	v_mul_lo_u32 v5, v0, 12
	v_sub_u32_e32 v5, v24, v5
	v_mad_i64_i32 v[6:7], s[8:9], v0, s38, v[2:3]
	v_lshlrev_b32_e32 v8, 3, v5
	v_lshl_add_u64 v[6:7], v[6:7], 0, s[10:11]
	v_ashrrev_i32_e32 v9, 31, v8
	v_lshl_add_u64 v[6:7], v[8:9], 1, v[6:7]
	v_add_co_u32_e32 v6, vcc, s5, v6
	v_mul_lo_u32 v0, v0, s36
	s_nop 0
	v_addc_co_u32_e32 v7, vcc, 0, v7, vcc
	global_load_dwordx4 v[160:163], v[6:7], off offset:2048
	v_lshl_add_u32 v175, v5, 4, v0
	v_add_u32_e32 v0, 0x400, v51
	v_mul_hi_i32 v5, v0, s31
	v_lshrrev_b32_e32 v6, 31, v5
	v_ashrrev_i32_e32 v5, 1, v5
	v_add_u32_e32 v5, v5, v6
	v_mul_lo_u32 v6, v5, 12
	v_sub_u32_e32 v0, v0, v6
	v_mad_i64_i32 v[6:7], s[8:9], v5, s38, v[2:3]
	v_lshlrev_b32_e32 v8, 3, v0
	v_lshl_add_u64 v[6:7], v[6:7], 0, s[10:11]
	v_ashrrev_i32_e32 v9, 31, v8
	v_lshl_add_u64 v[6:7], v[8:9], 1, v[6:7]
	v_add_co_u32_e32 v6, vcc, s5, v6
	v_mul_lo_u32 v5, v5, s36
	s_nop 0
	v_addc_co_u32_e32 v7, vcc, 0, v7, vcc
	global_load_dwordx4 v[164:167], v[6:7], off offset:2048
	v_lshl_add_u32 v176, v0, 4, v5
	v_add_u32_e32 v0, 0x500, v51
	v_mul_hi_i32 v5, v0, s31
	v_lshrrev_b32_e32 v6, 31, v5
	v_ashrrev_i32_e32 v5, 1, v5
	v_add_u32_e32 v5, v5, v6
	v_mul_lo_u32 v6, v5, 12
	v_sub_u32_e32 v0, v0, v6
	v_mad_i64_i32 v[2:3], s[8:9], v5, s38, v[2:3]
	v_lshlrev_b32_e32 v6, 3, v0
	v_lshl_add_u64 v[2:3], v[2:3], 0, s[10:11]
	v_ashrrev_i32_e32 v7, 31, v6
	v_lshl_add_u64 v[2:3], v[6:7], 1, v[2:3]
	v_add_co_u32_e32 v2, vcc, s5, v2
	s_movk_i32 s5, 0x80
	s_nop 0
	v_addc_co_u32_e32 v3, vcc, 0, v3, vcc
	global_load_dwordx4 v[168:171], v[2:3], off offset:2048
	v_mul_lo_u32 v2, v5, s36
	v_lshrrev_b32_e32 v3, 3, v51
	v_lshl_add_u32 v177, v0, 4, v2
	v_and_b32_e32 v52, 4, v3
	v_lshrrev_b32_e32 v3, 2, v51
	v_cmp_gt_u32_e32 vcc, s5, v51
	v_and_or_b32 v6, v3, 3, v52
	v_lshlrev_b32_e32 v3, 1, v51
	v_bfe_u32 v0, v51, 6, 1
	v_cndmask_b32_e64 v2, v210, 0, vcc
	v_and_b32_e32 v3, 32, v3
	v_or_b32_e32 v2, v2, v3
	v_lshlrev_b32_e32 v5, 6, v0
	v_or3_b32 v2, v2, v5, v4
	v_or_b32_e32 v7, v3, v4
	v_mad_u32_u24 v53, v6, s30, v2
	v_mad_u32_u24 v62, v6, s36, v7
	s_waitcnt vmcnt(5)
	ds_write_b128 v172, v[148:151] offset:36864
	s_waitcnt vmcnt(4)
	ds_write_b128 v173, v[152:155] offset:36864
	s_waitcnt vmcnt(3)
	ds_write_b128 v174, v[156:159] offset:36864
	s_waitcnt vmcnt(2)
	ds_write_b128 v175, v[160:163] offset:36864
	s_waitcnt vmcnt(1)
	ds_write_b128 v176, v[164:167] offset:36864
	s_waitcnt vmcnt(0)
	ds_write_b128 v177, v[168:171] offset:36864
	s_waitcnt lgkmcnt(0)
	s_barrier
	ds_read_b64_tr_b16 v[2:3], v53
	ds_read_b64_tr_b16 v[4:5], v53 offset:1152
	ds_read_b64_tr_b16 v[6:7], v62 offset:36864
	ds_read_b64_tr_b16 v[8:9], v62 offset:38528
	s_waitcnt lgkmcnt(0)
	v_mfma_f32_32x32x16_bf16 v[34:49], v[6:9], v[2:5], 0
	ds_read_b64_tr_b16 v[6:7], v62 offset:36928
	ds_read_b64_tr_b16 v[8:9], v62 offset:38592
	s_waitcnt lgkmcnt(0)
	v_mfma_f32_32x32x16_bf16 v[18:33], v[6:9], v[2:5], 0
	ds_read_b64_tr_b16 v[6:7], v62 offset:36992
	ds_read_b64_tr_b16 v[8:9], v62 offset:38656
	ds_read_b64_tr_b16 v[54:55], v53 offset:2304
	ds_read_b64_tr_b16 v[56:57], v53 offset:3456
	ds_read_b64_tr_b16 v[58:59], v62 offset:40192
	ds_read_b64_tr_b16 v[60:61], v62 offset:41856
	s_waitcnt lgkmcnt(0)
	v_mfma_f32_32x32x16_bf16 v[34:49], v[58:61], v[54:57], v[34:49]
	ds_read_b64_tr_b16 v[58:59], v62 offset:40256
	ds_read_b64_tr_b16 v[60:61], v62 offset:41920
	v_mfma_f32_32x32x16_bf16 v[2:17], v[6:9], v[2:5], 0
	s_waitcnt lgkmcnt(0)
	v_mfma_f32_32x32x16_bf16 v[18:33], v[58:61], v[54:57], v[18:33]
	ds_read_b64_tr_b16 v[58:59], v62 offset:40320
	ds_read_b64_tr_b16 v[60:61], v62 offset:41984
	s_waitcnt lgkmcnt(0)
	v_mfma_f32_32x32x16_bf16 v[2:17], v[58:61], v[54:57], v[2:17]
	ds_read_b64_tr_b16 v[54:55], v53 offset:4608
	ds_read_b64_tr_b16 v[56:57], v53 offset:5760
	ds_read_b64_tr_b16 v[58:59], v62 offset:43520
	ds_read_b64_tr_b16 v[60:61], v62 offset:45184
	s_waitcnt lgkmcnt(0)
	v_mfma_f32_32x32x16_bf16 v[34:49], v[58:61], v[54:57], v[34:49]
	ds_read_b64_tr_b16 v[58:59], v62 offset:43584
	ds_read_b64_tr_b16 v[60:61], v62 offset:45248
	s_waitcnt lgkmcnt(0)
	v_mfma_f32_32x32x16_bf16 v[18:33], v[58:61], v[54:57], v[18:33]
	ds_read_b64_tr_b16 v[58:59], v62 offset:43648
	ds_read_b64_tr_b16 v[60:61], v62 offset:45312
	s_waitcnt lgkmcnt(0)
	v_mfma_f32_32x32x16_bf16 v[2:17], v[58:61], v[54:57], v[2:17]
	ds_read_b64_tr_b16 v[54:55], v53 offset:6912
	ds_read_b64_tr_b16 v[56:57], v53 offset:8064
	ds_read_b64_tr_b16 v[58:59], v62 offset:46848
	ds_read_b64_tr_b16 v[60:61], v62 offset:48512
	s_waitcnt lgkmcnt(0)
	v_mfma_f32_32x32x16_bf16 v[34:49], v[58:61], v[54:57], v[34:49]
	ds_read_b64_tr_b16 v[58:59], v62 offset:46912
	ds_read_b64_tr_b16 v[60:61], v62 offset:48576
	s_waitcnt lgkmcnt(0)
	v_mfma_f32_32x32x16_bf16 v[18:33], v[58:61], v[54:57], v[18:33]
	ds_read_b64_tr_b16 v[58:59], v62 offset:46976
	ds_read_b64_tr_b16 v[60:61], v62 offset:48640
	s_waitcnt lgkmcnt(0)
	v_mfma_f32_32x32x16_bf16 v[2:17], v[58:61], v[54:57], v[2:17]
	ds_read_b64_tr_b16 v[54:55], v53 offset:9216
	ds_read_b64_tr_b16 v[56:57], v53 offset:10368
	ds_read_b64_tr_b16 v[58:59], v62 offset:50176
	ds_read_b64_tr_b16 v[60:61], v62 offset:51840
	s_waitcnt lgkmcnt(0)
	v_mfma_f32_32x32x16_bf16 v[34:49], v[58:61], v[54:57], v[34:49]
	ds_read_b64_tr_b16 v[58:59], v62 offset:50240
	ds_read_b64_tr_b16 v[60:61], v62 offset:51904
	s_waitcnt lgkmcnt(0)
	v_mfma_f32_32x32x16_bf16 v[18:33], v[58:61], v[54:57], v[18:33]
	ds_read_b64_tr_b16 v[58:59], v62 offset:50304
	ds_read_b64_tr_b16 v[60:61], v62 offset:51968
	s_waitcnt lgkmcnt(0)
	v_mfma_f32_32x32x16_bf16 v[2:17], v[58:61], v[54:57], v[2:17]
	ds_read_b64_tr_b16 v[54:55], v53 offset:11520
	ds_read_b64_tr_b16 v[56:57], v53 offset:12672
	ds_read_b64_tr_b16 v[58:59], v62 offset:53504
	ds_read_b64_tr_b16 v[60:61], v62 offset:55168
	s_waitcnt lgkmcnt(0)
	v_mfma_f32_32x32x16_bf16 v[34:49], v[58:61], v[54:57], v[34:49]
	ds_read_b64_tr_b16 v[58:59], v62 offset:53568
	ds_read_b64_tr_b16 v[60:61], v62 offset:55232
	s_waitcnt lgkmcnt(0)
	v_mfma_f32_32x32x16_bf16 v[18:33], v[58:61], v[54:57], v[18:33]
	ds_read_b64_tr_b16 v[58:59], v62 offset:53632
	ds_read_b64_tr_b16 v[60:61], v62 offset:55296
	s_waitcnt lgkmcnt(0)
	v_mfma_f32_32x32x16_bf16 v[2:17], v[58:61], v[54:57], v[2:17]
	ds_read_b64_tr_b16 v[54:55], v53 offset:13824
	ds_read_b64_tr_b16 v[56:57], v53 offset:14976
	ds_read_b64_tr_b16 v[58:59], v62 offset:56832
	ds_read_b64_tr_b16 v[60:61], v62 offset:58496
	s_waitcnt lgkmcnt(0)
	v_mfma_f32_32x32x16_bf16 v[34:49], v[58:61], v[54:57], v[34:49]
	ds_read_b64_tr_b16 v[58:59], v62 offset:56896
	ds_read_b64_tr_b16 v[60:61], v62 offset:58560
	s_waitcnt lgkmcnt(0)
	v_mfma_f32_32x32x16_bf16 v[18:33], v[58:61], v[54:57], v[18:33]
	ds_read_b64_tr_b16 v[58:59], v62 offset:56960
	ds_read_b64_tr_b16 v[60:61], v62 offset:58624
	s_waitcnt lgkmcnt(0)
	v_mfma_f32_32x32x16_bf16 v[2:17], v[58:61], v[54:57], v[2:17]
	ds_read_b64_tr_b16 v[54:55], v53 offset:16128
	ds_read_b64_tr_b16 v[56:57], v53 offset:17280
	ds_read_b64_tr_b16 v[58:59], v62 offset:60160
	ds_read_b64_tr_b16 v[60:61], v62 offset:61824
	v_and_b32_e32 v53, 31, v51
	v_lshl_or_b32 v0, v0, 5, v53
	v_cmp_gt_u32_e32 vcc, 48, v0
	s_waitcnt lgkmcnt(0)
	v_mfma_f32_32x32x16_bf16 v[34:49], v[58:61], v[54:57], v[34:49]
	ds_read_b64_tr_b16 v[58:59], v62 offset:60224
	ds_read_b64_tr_b16 v[60:61], v62 offset:61888
	s_waitcnt lgkmcnt(0)
	v_mfma_f32_32x32x16_bf16 v[18:33], v[58:61], v[54:57], v[18:33]
	ds_read_b64_tr_b16 v[58:59], v62 offset:60288
	ds_read_b64_tr_b16 v[60:61], v62 offset:61952
	s_waitcnt lgkmcnt(0)
	v_mfma_f32_32x32x16_bf16 v[2:17], v[58:61], v[54:57], v[2:17]
	s_and_saveexec_b64 s[8:9], vcc
	s_cbranch_execz .LBB0_66
	s_lshl_b32 s4, s4, 2
	s_or_b32 s4, s4, s29
	s_ashr_i32 s5, s4, 31
	v_ashrrev_i32_e32 v54, 7, v51
	s_lshl_b64 s[4:5], s[4:5], 6
	s_lshl_b32 s10, s28, 1
	s_or_b32 s4, s4, s10
	v_ashrrev_i32_e32 v55, 31, v54
	v_lshl_add_u64 v[54:55], s[4:5], 0, v[54:55]
	v_mov_b64_e32 v[56:57], s[0:1]
	s_movk_i32 s4, 0x4800
	v_mad_u64_u32 v[56:57], s[0:1], v54, s4, v[56:57]
	v_mad_i32_i24 v57, v55, s4, v57
	v_lshlrev_b32_e32 v0, 2, v0
	v_lshl_add_u64 v[54:55], v[56:57], 0, v[0:1]
	v_mul_u32_u24_e32 v0, 48, v52
	v_lshlrev_b32_e32 v0, 2, v0
	v_lshl_add_u64 v[52:53], v[54:55], 0, v[0:1]
	s_movk_i32 s0, 0x1000
	global_store_dword v[52:53], v34, off sc1
	global_store_dword v[52:53], v35, off offset:192 sc1
	global_store_dword v[52:53], v36, off offset:384 sc1
	global_store_dword v[52:53], v37, off offset:576 sc1
	global_store_dword v[52:53], v38, off offset:1536 sc1
	global_store_dword v[52:53], v39, off offset:1728 sc1
	global_store_dword v[52:53], v40, off offset:1920 sc1
	global_store_dword v[52:53], v41, off offset:2112 sc1
	global_store_dword v[52:53], v42, off offset:3072 sc1
	global_store_dword v[52:53], v43, off offset:3264 sc1
	global_store_dword v[52:53], v44, off offset:3456 sc1
	global_store_dword v[52:53], v45, off offset:3648 sc1
	v_add_co_u32_e32 v34, vcc, s0, v52
	s_movk_i32 s0, 0x2000
	s_nop 0
	v_addc_co_u32_e32 v35, vcc, 0, v53, vcc
	global_store_dword v[34:35], v46, off offset:512 sc1
	global_store_dword v[34:35], v47, off offset:704 sc1
	global_store_dword v[34:35], v48, off offset:896 sc1
	global_store_dword v[34:35], v49, off offset:1088 sc1
	global_store_dword v[34:35], v18, off offset:2048 sc1
	global_store_dword v[34:35], v19, off offset:2240 sc1
	global_store_dword v[34:35], v20, off offset:2432 sc1
	global_store_dword v[34:35], v21, off offset:2624 sc1
	global_store_dword v[34:35], v22, off offset:3584 sc1
	global_store_dword v[34:35], v23, off offset:3776 sc1
	global_store_dword v[34:35], v24, off offset:3968 sc1
	v_add_co_u32_e32 v18, vcc, s0, v52
	s_nop 1
	v_addc_co_u32_e32 v19, vcc, 0, v53, vcc
	global_store_dword v[18:19], v25, off offset:64 sc1
	global_store_dword v[18:19], v26, off offset:1024 sc1
	global_store_dword v[18:19], v27, off offset:1216 sc1
	global_store_dword v[18:19], v28, off offset:1408 sc1
	global_store_dword v[18:19], v29, off offset:1600 sc1
	global_store_dword v[18:19], v30, off offset:2560 sc1
	global_store_dword v[18:19], v31, off offset:2752 sc1
	global_store_dword v[18:19], v32, off offset:2944 sc1
	global_store_dword v[18:19], v33, off offset:3136 sc1
	v_add_co_u32_e32 v18, vcc, s73, v52
	s_nop 1
	v_addc_co_u32_e32 v19, vcc, 0, v53, vcc
	global_store_dword v[18:19], v2, off sc1
	global_store_dword v[18:19], v3, off offset:192 sc1
	global_store_dword v[18:19], v4, off offset:384 sc1
	global_store_dword v[18:19], v5, off offset:576 sc1
	global_store_dword v[18:19], v6, off offset:1536 sc1
	global_store_dword v[18:19], v7, off offset:1728 sc1
	global_store_dword v[18:19], v8, off offset:1920 sc1
	global_store_dword v[18:19], v9, off offset:2112 sc1
	global_store_dword v[18:19], v10, off offset:3072 sc1
	global_store_dword v[18:19], v11, off offset:3264 sc1
	global_store_dword v[18:19], v12, off offset:3456 sc1
	global_store_dword v[18:19], v13, off offset:3648 sc1
	v_add_co_u32_e32 v2, vcc, 0x4000, v52
	s_nop 1
	v_addc_co_u32_e32 v3, vcc, 0, v53, vcc
	global_store_dword v[2:3], v14, off offset:512 sc1
	global_store_dword v[2:3], v15, off offset:704 sc1
	global_store_dword v[2:3], v16, off offset:896 sc1
	global_store_dword v[2:3], v17, off offset:1088 sc1

.LBB0_187:
	s_mov_b32 s4, 1
	s_cmp_lt_i32 s71, s4
	s_mov_b64 s[4:5], -1
	s_cbranch_scc0 .LBB0_186
	s_mov_b64 s[4:5], s[12:13]
	s_mov_b64 s[4:5], s[14:15]
	s_mov_b64 s[4:5], s[16:17]
	s_mov_b64 s[4:5], s[18:19]
	s_mov_b64 s[4:5], s[20:21]
	s_mov_b64 s[4:5], s[22:23]
	s_mov_b64 s[4:5], s[24:25]
	s_mov_b64 s[4:5], s[26:27]
	v_readlane_b32 s36, v243, 22
	v_readlane_b32 s37, v243, 23
	s_mov_b64 s[4:5], s[36:37]
	v_readlane_b32 s38, v243, 24
	v_readlane_b32 s39, v243, 25
	s_mov_b64 s[4:5], s[38:39]
	v_readlane_b32 s40, v243, 26
	v_readlane_b32 s41, v243, 27
	s_mov_b64 s[4:5], s[40:41]
	v_readlane_b32 s42, v243, 28
	v_readlane_b32 s43, v243, 29
	s_mov_b64 s[4:5], s[42:43]
	v_readlane_b32 s44, v243, 30
	v_readlane_b32 s45, v243, 31
	s_mov_b64 s[4:5], s[44:45]
	v_readlane_b32 s46, v243, 32
	v_readlane_b32 s47, v243, 33
	s_mov_b64 s[4:5], s[46:47]
	v_readlane_b32 s48, v243, 34
	v_readlane_b32 s49, v243, 35
	s_mov_b64 s[4:5], s[48:49]
	v_readlane_b32 s50, v243, 36
	v_readlane_b32 s51, v243, 37
	s_mov_b64 s[4:5], s[50:51]
	s_mov_b64 s[4:5], s[52:53]
	s_mov_b64 s[6:7], s[54:55]
	s_mov_b64 s[4:5], s[56:57]
	s_mov_b64 s[4:5], s[58:59]
	s_mov_b64 s[4:5], s[60:61]
	s_mov_b64 s[4:5], s[62:63]
	v_readlane_b32 s36, v243, 5
	v_readlane_b32 s37, v243, 6
	s_mov_b64 s[28:29], s[64:65]
	s_mov_b64 s[4:5], s[66:67]
	s_mov_b64 s[34:35], s[36:37]
	v_readlane_b32 s38, v243, 7
	v_readlane_b32 s39, v243, 8
	s_mov_b64 s[34:35], s[38:39]
	v_readlane_b32 s40, v243, 9
	v_readlane_b32 s41, v243, 10
	s_mov_b64 s[34:35], s[40:41]
	v_readlane_b32 s84, v243, 1
	v_readlane_b32 s42, v243, 11
	v_readlane_b32 s43, v243, 12
	v_readlane_b32 s85, v243, 2
	s_mov_b64 s[34:35], s[42:43]
	s_mov_b64 s[82:83], s[84:85]
	v_readlane_b32 s86, v243, 3
	v_readlane_b32 s87, v243, 4
	s_add_u32 s82, s82, s8
	s_mov_b64 s[84:85], s[86:87]
	v_mov_b32_e32 v83, v200
	s_addc_u32 s83, s83, s9
	global_load_dword v112, v1, s[82:83] offset:8
	global_load_dword v113, v1, s[82:83] offset:24
	v_readlane_b32 s31, v242, 12
	s_add_u32 s31, s34, s31
	v_readlane_b32 s34, v242, 4
	s_addc_u32 s35, s35, s34
	s_add_u32 s82, s31, 0x1200000
	s_addc_u32 s83, s35, 0
	s_mov_b32 s36, 0x2aaaaaab
	s_add_u32 s34, s31, 0x1202400
	s_movk_i32 s31, 0x240
	v_mul_hi_i32 v84, v83, s36
	s_addc_u32 s35, s35, 0
	v_cmp_gt_i32_e32 vcc, s31, v83
	v_lshlrev_b32_e32 v78, 3, v83
	v_lshrrev_b32_e32 v85, 31, v84
	s_and_saveexec_b64 s[84:85], vcc
	s_cbranch_execz .LBB0_190
	v_mul_hi_i32 v2, v78, s36
	v_lshrrev_b32_e32 v3, 31, v2
	v_lshrrev_b32_e32 v2, 3, v2
	v_add_u32_e32 v2, v2, v3
	v_ashrrev_i32_e32 v79, 31, v78
	v_mul_lo_u32 v2, v2, 48
	v_lshlrev_b64 v[6:7], 1, v[78:79]
	v_sub_u32_e32 v8, v78, v2
	v_lshl_add_u64 v[2:3], s[82:83], 0, v[6:7]
	v_lshl_add_u64 v[134:135], s[34:35], 0, v[6:7]
	global_load_dwordx4 v[2:5], v[2:3], off
	global_load_dwordx4 v[130:133], v[134:135], off
	v_add_u32_e32 v0, v84, v85
	s_movk_i32 s31, 0x90
	v_mul_lo_u32 v0, v0, s31
	v_lshl_add_u32 v0, v8, 1, v0
	s_waitcnt vmcnt(1)
	ds_write_b128 v0, v[2:5] offset:22528
	s_waitcnt vmcnt(0)
	ds_write_b128 v0, v[130:133] offset:36352
.LBB0_190:
	s_or_b64 exec, exec, s[84:85]
	v_add_u32_e32 v79, 0x100, v83
	s_movk_i32 s31, 0x140
	v_mul_hi_i32 v86, v79, s36
	v_cmp_gt_i32_e32 vcc, s31, v83
	v_lshrrev_b32_e32 v87, 31, v86
	s_and_saveexec_b64 s[84:85], vcc
	s_cbranch_execz .LBB0_192
	v_lshlrev_b32_e32 v2, 3, v79
	v_mul_hi_i32 v3, v2, s36
	v_lshrrev_b32_e32 v4, 31, v3
	v_lshrrev_b32_e32 v3, 3, v3
	v_add_u32_e32 v3, v3, v4
	v_mul_lo_u32 v3, v3, 48
	v_sub_u32_e32 v8, v2, v3
	v_ashrrev_i32_e32 v3, 31, v2
	v_lshlrev_b64 v[6:7], 1, v[2:3]
	v_lshl_add_u64 v[2:3], s[82:83], 0, v[6:7]
	v_lshl_add_u64 v[134:135], s[34:35], 0, v[6:7]
	global_load_dwordx4 v[2:5], v[2:3], off
	global_load_dwordx4 v[130:133], v[134:135], off
	v_add_u32_e32 v0, v86, v87
	s_movk_i32 s31, 0x90
	v_mul_lo_u32 v0, v0, s31
	v_lshl_add_u32 v0, v8, 1, v0
	s_waitcnt vmcnt(1)
	ds_write_b128 v0, v[2:5] offset:22528
	s_waitcnt vmcnt(0)
	ds_write_b128 v0, v[130:133] offset:36352
.LBB0_192:
	s_or_b64 exec, exec, s[84:85]
	v_add_u32_e32 v88, 0x200, v83
	v_mul_hi_i32 v89, v88, s36
	v_cmp_gt_i32_e32 vcc, 64, v83
	s_mov_b32 s31, 0x2aaaaaab
	v_lshrrev_b32_e32 v90, 31, v89
	s_and_saveexec_b64 s[84:85], vcc
	s_movk_i32 s38, 0x1e00
	s_cbranch_execz .LBB0_185
	v_lshlrev_b32_e32 v2, 3, v88
	v_mul_hi_i32 v3, v2, s31
	v_lshrrev_b32_e32 v4, 31, v3
	v_lshrrev_b32_e32 v3, 3, v3
	v_add_u32_e32 v3, v3, v4
	v_mul_lo_u32 v3, v3, 48
	v_sub_u32_e32 v8, v2, v3
	v_ashrrev_i32_e32 v3, 31, v2
	v_lshlrev_b64 v[6:7], 1, v[2:3]
	v_lshl_add_u64 v[2:3], s[82:83], 0, v[6:7]
	v_lshl_add_u64 v[134:135], s[34:35], 0, v[6:7]
	global_load_dwordx4 v[2:5], v[2:3], off
	global_load_dwordx4 v[130:133], v[134:135], off
	v_add_u32_e32 v0, v89, v90
	s_movk_i32 s31, 0x90
	v_mul_lo_u32 v0, v0, s31
	v_lshl_add_u32 v0, v8, 1, v0
	s_waitcnt vmcnt(1)
	ds_write_b128 v0, v[2:5] offset:22528
	s_waitcnt vmcnt(0)
	ds_write_b128 v0, v[130:133] offset:36352
	s_branch .LBB0_185

.LBB0_314:
	v_lshl_add_u64 v[32:33], v[16:17], 0, s[94:95]
	v_lshl_add_u64 v[36:37], v[22:23], 0, s[94:95]
	global_load_dwordx4 v[28:31], v[32:33], off offset:16
	s_nop 0
	global_load_dwordx4 v[32:35], v[32:33], off
	s_nop 0
	global_load_dwordx4 v[48:51], v[36:37], off offset:16
	global_load_dwordx4 v[52:55], v[36:37], off
	v_lshl_add_u64 v[36:37], v[20:21], 0, s[94:95]
	global_load_dwordx4 v[56:59], v[36:37], off offset:16
	global_load_dwordx4 v[60:63], v[36:37], off
	v_lshl_add_u64 v[36:37], v[18:19], 0, s[94:95]
	global_load_dwordx4 v[64:67], v[36:37], off offset:16
	global_load_dwordx4 v[68:71], v[36:37], off
	s_waitcnt vmcnt(6)
	v_mov_b32_e32 v37, v32
	s_waitcnt vmcnt(4)
	v_mov_b32_e32 v73, v52
	v_mov_b32_e32 v3, v34
	s_waitcnt vmcnt(2)
	v_mov_b32_e32 v36, v60
	v_mov_b32_e32 v32, v61
	s_waitcnt vmcnt(0)
	v_mov_b32_e32 v72, v68
	v_pk_fma_f32 v[4:5], v[36:37], v[72:73], v[4:5]
	v_lshl_add_u64 v[36:37], v[14:15], 0, s[94:95]
	global_load_dwordx4 v[72:75], v[36:37], off offset:16
	global_load_dwordx4 v[76:79], v[36:37], off
	v_mov_b32_e32 v52, v69
	v_pk_fma_f32 v[4:5], v[32:33], v[52:53], v[4:5]
	v_mov_b32_e32 v32, v70
	v_mov_b32_e32 v33, v54
	v_mov_b32_e32 v34, v63
	v_mov_b32_e32 v54, v71
	s_add_u32 s94, s94, 32
	s_addc_u32 s95, s95, 0
	s_cmpk_lg_i32 s94, 0x80
	s_waitcnt vmcnt(0)
	v_max3_f32 v0, v2, |v76|, |v77|
	v_mov_b32_e32 v2, v62
	v_pk_fma_f32 v[2:3], v[2:3], v[32:33], v[4:5]
	v_mov_b32_e32 v4, v56
	v_pk_fma_f32 v[2:3], v[34:35], v[54:55], v[2:3]
	v_mov_b32_e32 v5, v28
	v_mov_b32_e32 v32, v64
	v_mov_b32_e32 v33, v48
	v_pk_fma_f32 v[2:3], v[4:5], v[32:33], v[2:3]
	v_mov_b32_e32 v28, v57
	v_mov_b32_e32 v48, v65
	v_max3_f32 v0, v0, |v78|, |v79|
	v_pk_fma_f32 v[2:3], v[28:29], v[48:49], v[2:3]
	v_mov_b32_e32 v4, v58
	v_mov_b32_e32 v5, v30
	v_mov_b32_e32 v28, v66
	v_mov_b32_e32 v29, v50
	v_max3_f32 v0, v0, |v72|, |v73|
	v_pk_fma_f32 v[2:3], v[4:5], v[28:29], v[2:3]
	v_mov_b32_e32 v30, v59
	v_mov_b32_e32 v50, v67
	v_pk_fma_f32 v[4:5], v[30:31], v[50:51], v[2:3]
	v_max3_f32 v2, v0, |v74|, |v75|
	s_cbranch_scc1 .LBB0_314
	global_load_dwordx4 v[80:83], v[24:25], off
	global_load_dwordx4 v[84:87], v[24:25], off offset:16
	global_load_dwordx4 v[88:91], v[24:25], off offset:32
	global_load_dwordx4 v[92:95], v[24:25], off offset:48
	global_load_dwordx4 v[96:99], v[24:25], off offset:64
	global_load_dwordx4 v[100:103], v[24:25], off offset:80
	global_load_dwordx4 v[104:107], v[24:25], off offset:96
	global_load_dwordx4 v[108:111], v[24:25], off offset:112
	global_load_dwordx4 v[112:115], v[24:25], off offset:128
	global_load_dwordx4 v[116:119], v[24:25], off offset:144
	global_load_dwordx4 v[120:123], v[24:25], off offset:160
	global_load_dwordx4 v[124:127], v[24:25], off offset:176
	global_load_dwordx4 v[128:131], v[24:25], off offset:192
	global_load_dwordx4 v[132:135], v[24:25], off offset:208
	global_load_dwordx4 v[136:139], v[24:25], off offset:224
	global_load_dwordx4 v[140:143], v[24:25], off offset:240
	s_mov_b64 s[4:5], 0
	s_mov_b32 s9, 0x3f2aaaab
	s_mov_b32 s39, 0x3f317218
	s_mov_b32 s40, 0x33800000
	s_waitcnt vmcnt(0)
	v_max_f32_e64 v3, |v80|, |v81|
	v_max3_f32 v3, v3, |v82|, |v83|
	v_max3_f32 v3, v3, |v84|, |v85|
	v_max3_f32 v3, v3, |v86|, |v87|
	v_max3_f32 v3, v3, |v88|, |v89|
	v_max3_f32 v3, v3, |v90|, |v91|
	v_max3_f32 v3, v3, |v92|, |v93|
	v_max3_f32 v3, v3, |v94|, |v95|
	v_max3_f32 v3, v3, |v96|, |v97|
	v_max3_f32 v3, v3, |v98|, |v99|
	v_max3_f32 v3, v3, |v100|, |v101|
	v_max3_f32 v3, v3, |v102|, |v103|
	v_max3_f32 v3, v3, |v104|, |v105|
	v_max3_f32 v3, v3, |v106|, |v107|
	v_max3_f32 v3, v3, |v108|, |v109|
	v_max3_f32 v3, v3, |v110|, |v111|
	v_max3_f32 v3, v3, |v112|, |v113|
	v_max3_f32 v3, v3, |v114|, |v115|
	v_max3_f32 v3, v3, |v116|, |v117|
	v_max3_f32 v3, v3, |v118|, |v119|
	v_max3_f32 v3, v3, |v120|, |v121|
	v_max3_f32 v3, v3, |v122|, |v123|
	v_max3_f32 v3, v3, |v124|, |v125|
	v_max3_f32 v3, v3, |v126|, |v127|
	v_max3_f32 v3, v3, |v128|, |v129|
	v_max3_f32 v3, v3, |v130|, |v131|
	v_max3_f32 v3, v3, |v132|, |v133|
	v_max3_f32 v3, v3, |v134|, |v135|
	v_max3_f32 v3, v3, |v136|, |v137|
	v_max3_f32 v3, v3, |v138|, |v139|
	v_max3_f32 v3, v3, |v140|, |v141|
	v_max3_f32 v3, v3, |v142|, |v143|
